# P1 tile order re-mapped: rounds 0-4 hold the 1280 full tiles, the half-empty last round holds only the 128 half-cost padded-column tiles
# speedup vs baseline: 1.0271x; 1.0271x over previous
;     DI bool next(int i, Unit& u) const {
;         const long L = (long)i * G + c; if (L >= nwg) return false;
;         int wgid = (int)L; { const int q = nwg / NXCD, r = nwg % NXCD, xcd = wgid % NXCD, off = wgid / NXCD; wgid = (xcd < r ? xcd * (q + 1) : r * (q + 1) + (xcd - r) * q) + off; }
;         const int nig = WGM * nN, gid = wgid / nig, fm = gid * WGM, gsz = (nM - fm) < WGM ? (nM - fm) : WGM;
;         u.pm = fm + ((wgid % nig) % gsz); u.pn = (wgid % nig) / gsz; return true;
; DI void gemm_phase(LAS unsigned char* lds, const Gemm g, const StaticOrder& S, const Epi& E) {
;     ...
;     if (!S.next(0, cur)) return;
.LBB0_166:
	s_or_b64 exec, exec, s[2:3]
	s_cmpk_lt_i32 s86, 0x580
	s_cselect_b64 s[2:3], -1, 0
	v_mov_b32_e32 v8, v167
	s_and_b64 vcc, exec, s[2:3]
	v_readfirstlane_b32 s18, v8
	s_cbranch_vccz .LBB0_168
	s_ashr_i32 s0, s86, 31
	s_lshr_b32 s0, s0, 29
	s_add_i32 s0, s86, s0
	s_ashr_i32 s1, s0, 3
	s_and_b32 s0, s0, -8
	s_sub_i32 s0, s86, s0
	s_cmp_lt_i32 s0, 0
	s_movk_i32 s4, 0xa1
	s_cselect_b32 s4, s4, 0xa0
	s_mul_i32 s0, s0, s4
	s_add_i32 s0, s0, s1
	s_mul_hi_i32 s1, s0, 0x66666667
	s_lshr_b32 s4, s1, 31
	s_ashr_i32 s1, s1, 4
	s_add_i32 s1, s1, s4
	s_lshl_b32 s4, s1, 2
	s_mul_i32 s1, s1, 40
	s_sub_i32 s0, s0, s1
	s_bfe_i32 s1, s0, 0x80000
	s_bfe_u32 s1, s1, 0x2000d
	s_add_i32 s1, s0, s1
	s_bfe_i32 s5, s1, 0x80000
	s_and_b32 s1, s1, 0xfc
	s_sub_i32 s0, s0, s1
	s_sext_i32_i16 s5, s5
	s_sext_i32_i8 s0, s0
	s_add_i32 s28, s4, s0
	s_ashr_i32 s4, s5, 2

;     DI bool next(int i, Unit& u) const {
;         const long L = (long)i * G + c; if (L >= nwg) return false;
;         int wgid = (int)L; { const int q = nwg / NXCD, r = nwg % NXCD, xcd = wgid % NXCD, off = wgid / NXCD; wgid = (xcd < r ? xcd * (q + 1) : r * (q + 1) + (xcd - r) * q) + off; }
;         const int nig = WGM * nN, gid = wgid / nig, fm = gid * WGM, gsz = (nM - fm) < WGM ? (nM - fm) : WGM;
;         u.pm = fm + ((wgid % nig) % gsz); u.pn = (wgid % nig) / gsz; return true;
; DI void gemm_phase(LAS unsigned char* lds, const Gemm g, const StaticOrder& S, const Epi& E) {
;     ...
;         const bool has_next = S.next(ui + 1, nxt);
.LBB0_174:
	s_add_i32 s42, s42, 1
	s_mul_i32 s2, s42, s94
	s_mul_hi_u32 s3, s42, s64
	s_add_i32 s3, s3, s2
	s_mul_i32 s2, s42, s64
	s_add_u32 s24, s2, s86
	s_addc_u32 s25, s3, s95
	v_cmp_gt_i64_e32 vcc, s[24:25], v[142:143]
	v_cmp_lt_i64_e64 s[2:3], s[24:25], v[140:141]
	s_cbranch_vccnz .LBB0_176
	s_cmpk_lt_i32 s24, 0x500
	s_cbranch_scc1 .Lp1_fulltile
	s_mov_b32 s20, 10
	s_add_i32 s22, s24, 0xfffffb00
	s_branch .LBB0_176
.Lp1_fulltile:
	s_ashr_i32 s5, s24, 31
	s_lshr_b32 s5, s5, 29
	s_add_i32 s5, s24, s5
	s_ashr_i32 s20, s5, 3
	s_and_b32 s5, s5, -8
	s_sub_i32 s5, s24, s5
	s_cmp_lt_i32 s5, 0
	s_cselect_b32 s21, s49, 0xa0
	s_mul_i32 s5, s5, s21
	s_add_i32 s5, s5, s20
	s_mul_hi_i32 s20, s5, 0x66666667
	s_lshr_b32 s21, s20, 31
	s_ashr_i32 s20, s20, 4
	s_add_i32 s20, s20, s21
	s_lshl_b32 s21, s20, 2
	s_sub_i32 s22, 0x80, s21
	s_min_i32 s22, s22, 4
	s_abs_i32 s23, s22
	v_cvt_f32_u32_e32 v0, s23
	s_sub_i32 s25, 0, s23
	s_mul_i32 s20, s20, 40
	s_sub_i32 s5, s5, s20
	v_rcp_iflag_f32_e32 v0, v0
	s_abs_i32 s20, s5
	s_xor_b32 s24, s5, s22
	s_ashr_i32 s24, s24, 31
	v_mul_f32_e32 v0, 0x4f7ffffe, v0
	v_cvt_u32_f32_e32 v0, v0
	s_nop 0
	v_readfirstlane_b32 s26, v0
	s_mul_i32 s25, s25, s26
	s_mul_hi_u32 s25, s26, s25
	s_add_i32 s26, s26, s25
	s_mul_hi_u32 s25, s20, s26
	s_mul_i32 s26, s25, s23
	s_sub_i32 s20, s20, s26
	s_add_i32 s27, s25, 1
	s_sub_i32 s26, s20, s23
	s_cmp_ge_u32 s20, s23
	s_cselect_b32 s25, s27, s25
	s_cselect_b32 s20, s26, s20
	s_add_i32 s26, s25, 1
	s_cmp_ge_u32 s20, s23
	s_cselect_b32 s20, s26, s25
	s_xor_b32 s20, s20, s24
	s_sub_i32 s20, s20, s24
	s_mul_i32 s22, s20, s22
	s_sub_i32 s5, s5, s22
	s_add_i32 s22, s21, s5
